# P6 row-scale table and unit remap now guarded on gridDim.x==256 (original path kept for other grids)
# speedup vs baseline: 1.0321x; 1.0004x over previous
; DI float ssq8(const float* p) { const f32x4 a = *(const f32x4*)p, b = *(const f32x4*)(p + 4); return ((a[0] + a[1]) + (a[2] + a[3])) + ((b[0] + b[1]) + (b[2] + b[3])); }
;     __host__ __device__ bool next(int i, Unit& u) const {
;         const long L = (long)i * G + c; if (L >= nwg) return false;
;         int wgid = (int)L; { const int q = nwg / NXCD, r = nwg % NXCD, xcd = wgid % NXCD, off = wgid / NXCD; wgid = (xcd < r ? xcd * (q + 1) : r * (q + 1) + (xcd - r) * q) + off; }
;         const int nig = WGM * nN, gid = wgid / nig, fm = gid * WGM, gsz = (nM - fm) < WGM ? (nM - fm) : WGM;
;         u.pm = fm + ((wgid % nig) % gsz); u.pn = (wgid % nig) / gsz; return true;
;     DI void operator()(const f32x4 (&acc)[2][2][4][2], const Unit& u, int wr, int wc, int fr, int fq) const {
;     ...
;         const int rbase = u.pm * 256 + wr * 64 + fr;
;         float rsv[8];
; #pragma unroll
;         for (int i = 0; i < 8; ++i) rsv[i] = ssq8(ssq + (size_t)(rbase + (i >> 2) * 128 + (i & 3) * 16) * 32 + 8 * fq);
; #pragma unroll
;         for (int i = 0; i < 8; ++i) { float sq = rsv[i]; sq += __shfl_xor(sq, 16); sq += __shfl_xor(sq, 32); rsv[i] = rsqrtf(sq * (1.f / 2048.f) + EPS_); }
.LBB0_783:
	s_andn2_b64 vcc, exec, s[4:5]
	s_cbranch_vccnz .LBB0_931
	s_cmpk_lg_i32 s58, 0x100
	s_cbranch_scc1 .Lp6_nomap0
	s_and_b32 s6, s2, 7
	s_lshr_b32 s6, s6, 1
	s_lshl_b32 s6, s6, 3
	s_bfe_u32 s8, s2, 0x30003
	s_add_i32 s6, s6, s8
	s_and_b32 s8, s2, 1
	s_lshl_b32 s8, s8, 2
	s_lshr_b32 s9, s2, 6
	s_add_i32 s8, s8, s9
.Lp6_nomap0:
	v_cmp_gt_u32_e32 vcc, 0x100, v253
	s_and_saveexec_b64 s[98:99], vcc
	s_cbranch_execz .Lrt6_skip
	s_lshl_b32 s100, s6, 15
	s_add_u32 s100, s100, s82
	s_addc_u32 s101, s83, 0
	s_add_u32 s100, s100, 0x100000
	s_addc_u32 s101, s101, 0
	v_lshlrev_b32_e32 v0, 7, v253
	global_load_dwordx4 v[4:7], v0, s[100:101]
	global_load_dwordx4 v[8:11], v0, s[100:101] offset:16
	global_load_dwordx4 v[12:15], v0, s[100:101] offset:32
	global_load_dwordx4 v[16:19], v0, s[100:101] offset:48
	global_load_dwordx4 v[20:23], v0, s[100:101] offset:64
	global_load_dwordx4 v[24:27], v0, s[100:101] offset:80
	global_load_dwordx4 v[28:31], v0, s[100:101] offset:96
	global_load_dwordx4 v[32:35], v0, s[100:101] offset:112
	s_waitcnt vmcnt(0)
	v_add_f32_e32 v36, v4, v5
	v_add_f32_e32 v37, v6, v7
	v_add_f32_e32 v36, v36, v37
	v_add_f32_e32 v37, v8, v9
	v_add_f32_e32 v38, v10, v11
	v_add_f32_e32 v37, v37, v38
	v_add_f32_e32 v40, v36, v37
	v_add_f32_e32 v36, v12, v13
	v_add_f32_e32 v37, v14, v15
	v_add_f32_e32 v36, v36, v37
	v_add_f32_e32 v37, v16, v17
	v_add_f32_e32 v38, v18, v19
	v_add_f32_e32 v37, v37, v38
	v_add_f32_e32 v41, v36, v37
	v_add_f32_e32 v36, v20, v21
	v_add_f32_e32 v37, v22, v23
	v_add_f32_e32 v36, v36, v37
	v_add_f32_e32 v37, v24, v25
	v_add_f32_e32 v38, v26, v27
	v_add_f32_e32 v37, v37, v38
	v_add_f32_e32 v42, v36, v37
	v_add_f32_e32 v36, v28, v29
	v_add_f32_e32 v37, v30, v31
	v_add_f32_e32 v36, v36, v37
	v_add_f32_e32 v37, v32, v33
	v_add_f32_e32 v38, v34, v35
	v_add_f32_e32 v37, v37, v38
	v_add_f32_e32 v43, v36, v37
	v_add_f32_e32 v36, v40, v41
	v_add_f32_e32 v37, v42, v43
	v_add_f32_e32 v36, v36, v37
	v_lshlrev_b32_e32 v1, 2, v253
	v_add_u32_e32 v1, 0x20400, v1
	ds_write_b32 v1, v36

; template <class Epi, class Sched>
; __device__ __forceinline__ void gemm_phase(LAS unsigned char* lds, const Gemm g, const Sched& S, const Epi& E) {
;     ...
;         const bool has_next = S.next(ui + 1, nxt);
;         const char* nA = has_next ? (const char*)g.A + (size_t)nxt.pm * tsA : cA; const char* nB = has_next ? (const char*)g.Bt + (size_t)nxt.pn * tsB : cB;
;     ...
; #pragma unroll
;         for (int a = 0; a < 2; ++a)
; #pragma unroll
;             for (int b = 0; b < 2; ++b)
; #pragma unroll
;                 for (int m = 0; m < 4; ++m)
; #pragma unroll
;                     for (int n = 0; n < 2; ++n) acc[a][b][m][n] = (f32x4){0.f, 0.f, 0.f, 0.f};
;         cur = nxt; cA = nA; cB = nB; ++ui;
.LBB0_795:
	s_cmpk_lg_i32 s58, 0x100
	s_cbranch_scc1 .Lp6_nomap1
	s_and_b32 s34, s2, 7
	s_lshr_b32 s34, s34, 1
	s_lshl_b32 s34, s34, 3
	s_bfe_u32 s7, s2, 0x30003
	s_add_i32 s34, s34, s7
	s_lshl_b32 s30, s52, 3
	s_and_b32 s7, s2, 1
	s_lshl_b32 s7, s7, 2
	s_add_i32 s30, s30, s7
	s_lshr_b32 s7, s2, 6
	s_add_i32 s30, s30, s7

; DI float ssq8(const float* p) { const f32x4 a = *(const f32x4*)p, b = *(const f32x4*)(p + 4); return ((a[0] + a[1]) + (a[2] + a[3])) + ((b[0] + b[1]) + (b[2] + b[3])); }
;     DI void operator()(const f32x4 (&acc)[2][2][4][2], const Unit& u, int wr, int wc, int fr, int fq) const {
;         const int seg = u.pn >> 3, colt = (u.pn & 7) * 256;
;         const size_t dsto = (size_t)(seg == 0) * WS_Q2 + (size_t)(seg == 2) * WS_IV + (size_t)(seg == 3) * WS_G2;
;         bf16_t* dst = (bf16_t*)(ws + dsto);
;         const int rbase = u.pm * 256 + wr * 64 + fr;
;         float rsv[8];
; #pragma unroll
;         for (int i = 0; i < 8; ++i) rsv[i] = ssq8(ssq + (size_t)(rbase + (i >> 2) * 128 + (i & 3) * 16) * 32 + 8 * fq);
; #pragma unroll
;         for (int i = 0; i < 8; ++i) { float sq = rsv[i]; sq += __shfl_xor(sq, 16); sq += __shfl_xor(sq, 32); rsv[i] = rsqrtf(sq * (1.f / 2048.f) + EPS_); }
.LBB0_799:
	s_ashr_i32 s7, s8, 3
	s_lshl_b32 s9, s8, 8
	s_cmp_lt_u32 s8, 8
	s_cselect_b32 s8, 0x4c80000, 0
	s_cmp_lg_u32 s7, 2
	s_cselect_b64 s[42:43], -1, 0
	s_cmp_eq_u32 s7, 2
	s_cselect_b32 s10, 0xcc80000, 0
	s_add_u32 s8, s82, s8
	s_addc_u32 s11, s83, 0
	s_add_u32 s8, s8, s10
	s_addc_u32 s41, s11, 0
	s_lshl_b32 s35, s6, 8
	s_add_i32 s35, s35, s53
	v_or_b32_e32 v152, s35, v138
	v_ashrrev_i32_e32 v153, 31, v152
	v_lshlrev_b64 v[154:155], 7, v[152:153]
	v_or_b32_e32 v168, 16, v152
	v_lshl_add_u64 v[158:159], v[140:141], 0, v[154:155]
	v_ashrrev_i32_e32 v169, 31, v168
	s_cmpk_lg_i32 s58, 0x100
	s_cbranch_scc1 .Lp6_orig
	v_mov_b32_e32 v154, 0
	v_mov_b32_e32 v155, 0
	v_mov_b32_e32 v156, 0
	v_mov_b32_e32 v157, 0
	v_mov_b32_e32 v162, 0
	v_mov_b32_e32 v163, 0
	v_mov_b32_e32 v164, 0
	v_mov_b32_e32 v165, 0
	v_lshlrev_b64 v[158:159], 7, v[168:169]
	v_or_b32_e32 v166, 32, v152
	v_lshl_add_u64 v[158:159], v[140:141], 0, v[158:159]
	v_ashrrev_i32_e32 v167, 31, v166
	v_mov_b32_e32 v170, 0
	v_mov_b32_e32 v171, 0
	v_mov_b32_e32 v172, 0
	v_mov_b32_e32 v173, 0
	v_mov_b32_e32 v174, 0
	v_mov_b32_e32 v175, 0
	v_mov_b32_e32 v176, 0
	v_mov_b32_e32 v177, 0
	v_lshlrev_b64 v[158:159], 7, v[166:167]
	v_or_b32_e32 v160, 48, v152
	v_lshl_add_u64 v[158:159], v[140:141], 0, v[158:159]
	v_ashrrev_i32_e32 v161, 31, v160
	v_mov_b32_e32 v178, 0
	v_mov_b32_e32 v179, 0
	v_mov_b32_e32 v180, 0
	v_mov_b32_e32 v181, 0
	v_mov_b32_e32 v186, 0
	v_mov_b32_e32 v187, 0
	v_mov_b32_e32 v188, 0
	v_mov_b32_e32 v189, 0
	v_lshlrev_b64 v[158:159], 7, v[160:161]
	v_lshl_add_u64 v[158:159], v[140:141], 0, v[158:159]
	v_mov_b32_e32 v190, 0
	v_mov_b32_e32 v191, 0
	v_mov_b32_e32 v192, 0
	v_mov_b32_e32 v193, 0
	v_mov_b32_e32 v194, 0
	v_mov_b32_e32 v195, 0
	v_mov_b32_e32 v196, 0
	v_mov_b32_e32 v197, 0
	v_add_u32_e32 v158, 0x80, v152
	v_ashrrev_i32_e32 v159, 31, v158
	v_lshlrev_b64 v[198:199], 7, v[158:159]
	v_add_u32_e32 v206, 0x90, v152
	v_lshl_add_u64 v[202:203], v[140:141], 0, v[198:199]
	v_ashrrev_i32_e32 v207, 31, v206
	v_mov_b32_e32 v198, 0
	v_mov_b32_e32 v199, 0
	v_mov_b32_e32 v200, 0
	v_mov_b32_e32 v201, 0
	s_nop 0
	v_mov_b32_e32 v202, 0
	v_mov_b32_e32 v203, 0
	v_mov_b32_e32 v204, 0
	v_mov_b32_e32 v205, 0
	v_lshlrev_b64 v[206:207], 7, v[206:207]
	v_add_u32_e32 v214, 0xa0, v152
	v_lshl_add_u64 v[210:211], v[140:141], 0, v[206:207]
	v_ashrrev_i32_e32 v215, 31, v214
	v_mov_b32_e32 v206, 0
	v_mov_b32_e32 v207, 0
	v_mov_b32_e32 v208, 0
	v_mov_b32_e32 v209, 0
	s_nop 0
	v_mov_b32_e32 v210, 0
	v_mov_b32_e32 v211, 0
	v_mov_b32_e32 v212, 0
	v_mov_b32_e32 v213, 0
	v_lshlrev_b64 v[214:215], 7, v[214:215]
	v_lshl_add_u64 v[218:219], v[140:141], 0, v[214:215]
	v_mov_b32_e32 v214, 0
	v_mov_b32_e32 v215, 0
	v_mov_b32_e32 v216, 0
	v_mov_b32_e32 v217, 0
	s_nop 0
	v_mov_b32_e32 v218, 0
	v_mov_b32_e32 v219, 0
	v_mov_b32_e32 v220, 0
	v_mov_b32_e32 v221, 0
	v_add_u32_e32 v222, 0xb0, v152
	v_ashrrev_i32_e32 v223, 31, v222
	v_lshlrev_b64 v[222:223], 7, v[222:223]
	v_lshl_add_u64 v[226:227], v[140:141], 0, v[222:223]
	v_mov_b32_e32 v222, 0
	v_mov_b32_e32 v223, 0
	v_mov_b32_e32 v224, 0
	v_mov_b32_e32 v225, 0
	s_nop 0
	v_mov_b32_e32 v226, 0
	v_mov_b32_e32 v227, 0
	v_mov_b32_e32 v228, 0
	v_mov_b32_e32 v229, 0
	v_and_b32_e32 v230, 0xff, v152
	v_lshlrev_b32_e32 v230, 2, v230
	v_add_u32_e32 v230, 0x20400, v230
	ds_read_b32 v154, v230
	ds_read_b32 v170, v230 offset:64
	ds_read_b32 v178, v230 offset:128
	ds_read_b32 v190, v230 offset:192
	ds_read_b32 v198, v230 offset:512
	ds_read_b32 v206, v230 offset:576
	ds_read_b32 v214, v230 offset:640
	ds_read_b32 v222, v230 offset:704
	s_cmp_eq_u32 s7, 3
	s_cselect_b32 s6, 0x400000, 0
	s_and_b32 s31, s9, 0x700
	s_add_u32 s40, s8, s6
	s_addc_u32 s41, s41, 0
	s_cmp_lg_u32 s7, 1
	s_cselect_b64 s[6:7], -1, 0
	s_mov_b64 s[8:9], -1
	s_waitcnt lgkmcnt(0)
	v_and_b32_e32 v231, 48, v252
	v_cmp_eq_u32_e32 vcc, 0, v231
	s_nop 1
	v_cndmask_b32_e32 v154, 0, v154, vcc
	v_cndmask_b32_e32 v170, 0, v170, vcc
	v_cndmask_b32_e32 v178, 0, v178, vcc
	v_cndmask_b32_e32 v190, 0, v190, vcc
	v_cndmask_b32_e32 v198, 0, v198, vcc
	v_cndmask_b32_e32 v206, 0, v206, vcc
	v_cndmask_b32_e32 v214, 0, v214, vcc
	v_cndmask_b32_e32 v222, 0, v222, vcc
	s_branch .Lp6_join
.Lp6_orig:
	global_load_dwordx4 v[154:157], v[158:159], off
	global_load_dwordx4 v[162:165], v[158:159], off offset:16
	v_lshlrev_b64 v[158:159], 7, v[168:169]
	v_or_b32_e32 v166, 32, v152
	v_lshl_add_u64 v[158:159], v[140:141], 0, v[158:159]
	v_ashrrev_i32_e32 v167, 31, v166
	global_load_dwordx4 v[170:173], v[158:159], off
	global_load_dwordx4 v[174:177], v[158:159], off offset:16
	v_lshlrev_b64 v[158:159], 7, v[166:167]
	v_or_b32_e32 v160, 48, v152
	v_lshl_add_u64 v[158:159], v[140:141], 0, v[158:159]
	v_ashrrev_i32_e32 v161, 31, v160
	global_load_dwordx4 v[178:181], v[158:159], off
	global_load_dwordx4 v[186:189], v[158:159], off offset:16
	v_lshlrev_b64 v[158:159], 7, v[160:161]
	v_lshl_add_u64 v[158:159], v[140:141], 0, v[158:159]
	global_load_dwordx4 v[190:193], v[158:159], off
	global_load_dwordx4 v[194:197], v[158:159], off offset:16
	v_add_u32_e32 v158, 0x80, v152
	v_ashrrev_i32_e32 v159, 31, v158
	v_lshlrev_b64 v[198:199], 7, v[158:159]
	v_add_u32_e32 v206, 0x90, v152
	v_lshl_add_u64 v[202:203], v[140:141], 0, v[198:199]
	v_ashrrev_i32_e32 v207, 31, v206
	global_load_dwordx4 v[198:201], v[202:203], off
	s_nop 0
	global_load_dwordx4 v[202:205], v[202:203], off offset:16
	v_lshlrev_b64 v[206:207], 7, v[206:207]
	v_add_u32_e32 v214, 0xa0, v152
	v_lshl_add_u64 v[210:211], v[140:141], 0, v[206:207]
	v_ashrrev_i32_e32 v215, 31, v214
	global_load_dwordx4 v[206:209], v[210:211], off
	s_nop 0
	global_load_dwordx4 v[210:213], v[210:211], off offset:16
	v_lshlrev_b64 v[214:215], 7, v[214:215]
	v_lshl_add_u64 v[218:219], v[140:141], 0, v[214:215]
	global_load_dwordx4 v[214:217], v[218:219], off
	s_nop 0
	global_load_dwordx4 v[218:221], v[218:219], off offset:16
	v_add_u32_e32 v222, 0xb0, v152
	v_ashrrev_i32_e32 v223, 31, v222
	v_lshlrev_b64 v[222:223], 7, v[222:223]
	v_lshl_add_u64 v[226:227], v[140:141], 0, v[222:223]
	global_load_dwordx4 v[222:225], v[226:227], off
	s_nop 0
	global_load_dwordx4 v[226:229], v[226:227], off offset:16
	s_cmp_eq_u32 s7, 3
	s_cselect_b32 s6, 0x400000, 0
	s_and_b32 s31, s9, 0x700
	s_add_u32 s40, s8, s6
	s_addc_u32 s41, s41, 0
	s_cmp_lg_u32 s7, 1
	s_cselect_b64 s[6:7], -1, 0
	s_mov_b64 s[8:9], -1
	s_waitcnt vmcnt(0)
; DI unsigned pkh2(float lo, float hi) { f32x2 v = {lo, hi}; h2_t b = __builtin_convertvector(v, h2_t); return __builtin_bit_cast(unsigned, b); }
; DI u32x4 pack8(const f32x4 a, const f32x4 b) { u32x4 w; w.x = pk2(a[0], a[1]); w.y = pk2(a[2], a[3]); w.z = pk2(b[0], b[1]); w.w = pk2(b[2], b[3]); return w; }
; #define EPI_FENCE() asm volatile("" ::: "memory")
;     DI void operator()(const f32x4 (&acc)[2][2][4][2], const Unit& u, int wr, int wc, int fr, int fq) const {
;     ...
;         for (int i = 0; i < 8; ++i) rsv[i] = ssq8(ssq + (size_t)(rbase + (i >> 2) * 128 + (i & 3) * 16) * 32 + 8 * fq);
; #pragma unroll
;         for (int i = 0; i < 8; ++i) { float sq = rsv[i]; sq += __shfl_xor(sq, 16); sq += __shfl_xor(sq, 32); rsv[i] = rsqrtf(sq * (1.f / 2048.f) + EPS_); }
;         EPI_FENCE();
; #pragma unroll
;         for (int ai = 0; ai < 2; ++ai)
; #pragma unroll
;             for (int m = 0; m < 4; ++m) {
;                 const int r = rbase + ai * 128 + m * 16;
;                 const float rs = rsv[ai * 4 + m];
; #pragma unroll
;                 for (int bj = 0; bj < 2; ++bj) {
;                     const int cc = colt + bj * 128 + wc * 32 + 8 * fq;
;                     const f32x4 v0 = acc[ai][bj][m][0] * rs, v1 = acc[ai][bj][m][1] * rs;
;                     const size_t off = (size_t)r * DM + cc;
;                     if (seg == 2) {
;                         const int bb = r >> 12, tt = r & (SEQ - 1), ch = tt >> 6, sl = tt & 63, hh = cc >> 7, vv0 = cc & 127;
;                         bf16_t* vb = dst + ((size_t)(((bb * 16 + hh) * 64 + ch) * 128 + vv0)) * 64 + sl;
;                         const u32x4 w = pack8(v0, v1);
;                         vb[0 * 64] = (bf16_t)(w.x & 0xffff); vb[1 * 64] = (bf16_t)(w.x >> 16);
;                         vb[2 * 64] = (bf16_t)(w.y & 0xffff); vb[3 * 64] = (bf16_t)(w.y >> 16);
;                         vb[4 * 64] = (bf16_t)(w.z & 0xffff); vb[5 * 64] = (bf16_t)(w.z >> 16);
;                         vb[6 * 64] = (bf16_t)(w.w & 0xffff); vb[7 * 64] = (bf16_t)(w.w >> 16);
;                     } else if (seg == 1) {
;                         u32x4 w; w.x = pkh2(v0[0], v0[1]); w.y = pkh2(v0[2], v0[3]); w.z = pkh2(v1[0], v1[1]); w.w = pkh2(v1[2], v1[3]);
;                         *(u32x4*)(LOGF + off) = w;
;                     } else {
;                         *(u32x4*)(dst + off) = pack8(v0, v1);
.Lp6_join:
	v_mov_b32_e32 v230, v154
	v_mov_b32_e32 v231, v162
	v_mov_b32_e32 v162, v155
	v_mov_b32_e32 v154, v156
	v_mov_b32_e32 v155, v164
	v_mov_b32_e32 v164, v157
	v_pk_add_f32 v[156:157], v[230:231], v[162:163]
	v_pk_add_f32 v[154:155], v[154:155], v[164:165]
	v_mov_b32_e32 v162, v170
	v_mov_b32_e32 v163, v174
	v_mov_b32_e32 v174, v171
	v_mov_b32_e32 v164, v172
	v_mov_b32_e32 v165, v176
	v_mov_b32_e32 v176, v173
	v_mov_b32_e32 v170, v178
	v_mov_b32_e32 v171, v186
	v_mov_b32_e32 v186, v179
	v_mov_b32_e32 v172, v180
	v_mov_b32_e32 v173, v188
	v_mov_b32_e32 v188, v181
	v_mov_b32_e32 v178, v190
	v_mov_b32_e32 v179, v194
	v_mov_b32_e32 v194, v191
	v_mov_b32_e32 v180, v192
	v_mov_b32_e32 v181, v196
	v_mov_b32_e32 v196, v193
	v_pk_add_f32 v[154:155], v[156:157], v[154:155]
	v_pk_add_f32 v[156:157], v[162:163], v[174:175]
	v_pk_add_f32 v[162:163], v[164:165], v[176:177]
	v_pk_add_f32 v[164:165], v[170:171], v[186:187]
	v_pk_add_f32 v[170:171], v[172:173], v[188:189]
	v_pk_add_f32 v[172:173], v[178:179], v[194:195]
	v_pk_add_f32 v[156:157], v[156:157], v[162:163]
	v_pk_add_f32 v[162:163], v[164:165], v[170:171]
	v_pk_add_f32 v[164:165], v[180:181], v[196:197]
	v_mov_b32_e32 v170, v198
	v_pk_add_f32 v[164:165], v[172:173], v[164:165]
	v_mov_b32_e32 v171, v202
	v_mov_b32_e32 v202, v199
	v_mov_b32_e32 v172, v200
	v_mov_b32_e32 v173, v204
	v_mov_b32_e32 v204, v201
	v_pk_add_f32 v[170:171], v[170:171], v[202:203]
	v_pk_add_f32 v[172:173], v[172:173], v[204:205]
	v_and_b32_e32 v174, 64, v185
	v_pk_add_f32 v[176:177], v[170:171], v[172:173]
	v_mov_b32_e32 v170, v206
	v_mov_b32_e32 v171, v210
	v_mov_b32_e32 v210, v207
	v_mov_b32_e32 v172, v208
	v_mov_b32_e32 v173, v212
	v_mov_b32_e32 v212, v209
	v_pk_add_f32 v[170:171], v[170:171], v[210:211]
	v_pk_add_f32 v[172:173], v[172:173], v[212:213]
	v_add_u32_e32 v178, 64, v174
	v_pk_add_f32 v[180:181], v[170:171], v[172:173]
	v_mov_b32_e32 v170, v214
	v_mov_b32_e32 v171, v218
	v_mov_b32_e32 v218, v215
	v_mov_b32_e32 v172, v216
	v_mov_b32_e32 v173, v220
	v_mov_b32_e32 v220, v217
	v_pk_add_f32 v[170:171], v[170:171], v[218:219]
	v_pk_add_f32 v[172:173], v[172:173], v[220:221]
	v_mov_b32_e32 v174, v156
	v_pk_add_f32 v[186:187], v[170:171], v[172:173]
	v_xor_b32_e32 v173, 16, v185
	v_cmp_lt_i32_e32 vcc, v173, v178
	v_mov_b32_e32 v175, v154
	v_mov_b32_e32 v154, v157
	v_cndmask_b32_e32 v173, v185, v173, vcc
	v_lshlrev_b32_e32 v179, 2, v173
	v_pk_add_f32 v[154:155], v[174:175], v[154:155]
	ds_bpermute_b32 v157, v179, v155
	ds_bpermute_b32 v156, v179, v154
	v_xor_b32_e32 v173, 32, v185
	v_cmp_lt_i32_e32 vcc, v173, v178
	v_mov_b32_e32 v170, v222
	v_mov_b32_e32 v171, v226
	v_cndmask_b32_e32 v173, v185, v173, vcc
	v_lshlrev_b32_e32 v190, 2, v173
	s_waitcnt lgkmcnt(0)
	v_pk_add_f32 v[154:155], v[154:155], v[156:157]
	ds_bpermute_b32 v157, v190, v155
	ds_bpermute_b32 v156, v190, v154
	v_mov_b32_e32 v226, v223
	v_mov_b32_e32 v172, v224
	v_mov_b32_e32 v173, v228
	v_mov_b32_e32 v228, v225
	s_waitcnt lgkmcnt(0)
	v_pk_add_f32 v[154:155], v[154:155], v[156:157]
	v_pk_add_f32 v[170:171], v[170:171], v[226:227]
	v_pk_fma_f32 v[174:175], v[154:155], s[0:1], v[150:151] op_sel_hi:[1,0,0]
	v_pk_add_f32 v[172:173], v[172:173], v[228:229]
	v_mul_f32_e32 v154, 0x4b800000, v175
	v_cmp_gt_f32_e32 vcc, s68, v175
	v_pk_add_f32 v[188:189], v[170:171], v[172:173]
	v_mov_b32_e32 v155, v162
	v_cndmask_b32_e32 v154, v175, v154, vcc
	v_rsq_f32_e32 v170, v154
	v_mov_b32_e32 v154, v164
	v_mov_b32_e32 v162, v165
	v_pk_add_f32 v[154:155], v[154:155], v[162:163]
	ds_bpermute_b32 v157, v179, v155
	ds_bpermute_b32 v156, v179, v154
	v_mul_f32_e32 v162, 0x45800000, v170
	v_cndmask_b32_e32 v178, v170, v162, vcc
	v_mov_b32_e32 v162, v188
	v_mov_b32_e32 v163, v186
	s_waitcnt lgkmcnt(0)
	v_pk_add_f32 v[170:171], v[154:155], v[156:157]
	v_mov_b32_e32 v154, v180
	v_mov_b32_e32 v155, v176
	v_mov_b32_e32 v176, v181
	v_mov_b32_e32 v186, v189
	v_pk_add_f32 v[154:155], v[154:155], v[176:177]
	v_pk_add_f32 v[176:177], v[162:163], v[186:187]
	ds_bpermute_b32 v157, v179, v155
	ds_bpermute_b32 v156, v179, v154
	ds_bpermute_b32 v181, v179, v177
	ds_bpermute_b32 v180, v179, v176
	ds_bpermute_b32 v173, v190, v171
	ds_bpermute_b32 v172, v190, v170
	s_waitcnt lgkmcnt(4)
	v_pk_add_f32 v[162:163], v[154:155], v[156:157]
	ds_bpermute_b32 v165, v190, v163
	s_waitcnt lgkmcnt(3)
	v_pk_add_f32 v[154:155], v[176:177], v[180:181]
	ds_bpermute_b32 v164, v190, v162
	ds_bpermute_b32 v157, v190, v155
	ds_bpermute_b32 v156, v190, v154
	v_cmp_gt_f32_e64 s[10:11], s68, v174
	v_lshlrev_b64 v[176:177], 11, v[152:153]
	v_or_b32_e32 v175, s31, v151
	v_pk_mul_f32 v[126:127], v[126:127], v[178:179] op_sel_hi:[1,0]
	v_pk_mul_f32 v[124:125], v[124:125], v[178:179] op_sel_hi:[1,0]
	v_pk_mul_f32 v[122:123], v[122:123], v[178:179] op_sel_hi:[1,0]
	v_pk_mul_f32 v[180:181], v[120:121], v[178:179] op_sel_hi:[1,0]
	s_and_b64 vcc, exec, s[42:43]
	s_cbranch_vccz .LBB0_805
	v_or_b32_e32 v120, v176, v175
	v_mov_b32_e32 v121, v177
	s_and_b64 vcc, exec, s[6:7]
	s_cbranch_vccz .LBB0_802
	v_cvt_pk_bf16_f32 v186, v124, v125
	v_cvt_pk_bf16_f32 v187, v126, v127
	v_cvt_pk_bf16_f32 v188, v180, v181
	v_cvt_pk_bf16_f32 v189, v122, v123
	v_lshl_add_u64 v[190:191], v[120:121], 1, s[40:41]
	global_store_dwordx4 v[190:191], v[186:189], off
	s_mov_b64 s[8:9], 0
